# speedup vs baseline: 1.0024x; 1.0009x over previous
.LBB0_368:
	v_mfma_f32_16x16x32_bf16 v[4:7], v[120:123], v[152:155], v[4:7]
	v_mfma_f32_16x16x32_bf16 v[0:3], v[124:127], v[152:155], v[0:3]
	v_mfma_f32_16x16x32_bf16 v[4:7], v[112:115], v[156:159], v[4:7]
	v_mfma_f32_16x16x32_bf16 v[0:3], v[116:119], v[156:159], v[0:3]
	s_and_b64 vcc, exec, s[0:1]
	s_mov_b32 s23, s21
	s_cbranch_vccnz .LBB0_392
.Lh1a_top:
	v_mfma_f32_16x16x32_bf16 v[4:7], v[120:123], v[184:187], v[4:7]
	v_mfma_f32_16x16x32_bf16 v[0:3], v[124:127], v[184:187], v[0:3]
	v_mfma_f32_16x16x32_bf16 v[4:7], v[112:115], v[188:191], v[4:7]
	v_mfma_f32_16x16x32_bf16 v[0:3], v[116:119], v[188:191], v[0:3]

.LBB0_373:
	s_waitcnt lgkmcnt(8)
	ds_read_b64_tr_b16 v[240:241], v212 offset:2048
	ds_read_b64_tr_b16 v[242:243], v212 offset:6144
	ds_read_b64_tr_b16 v[244:245], v212 offset:10240
	ds_read_b64_tr_b16 v[246:247], v212 offset:14336
	v_mfma_f32_16x16x32_bf16 v[52:55], v[120:123], v[136:139], v[52:55]
	v_exp_f32_e32 v162, v84
	v_mfma_f32_16x16x32_bf16 v[48:51], v[124:127], v[136:139], v[48:51]
	v_exp_f32_e32 v163, v85
	v_mfma_f32_16x16x32_bf16 v[52:55], v[112:115], v[148:151], v[52:55]
	v_exp_f32_e32 v161, v86
	v_mfma_f32_16x16x32_bf16 v[48:51], v[116:119], v[148:151], v[48:51]
	v_exp_f32_e32 v160, v87
	v_exp_f32_e32 v167, v96
	s_waitcnt lgkmcnt(8)
	ds_read_b64_tr_b16 v[128:129], v213 offset:2048
	ds_read_b64_tr_b16 v[130:131], v213 offset:6144
	ds_read_b64_tr_b16 v[132:133], v213 offset:10240
	ds_read_b64_tr_b16 v[134:135], v213 offset:14336
	v_mfma_f32_16x16x32_bf16 v[44:47], v[120:123], v[152:155], v[44:47]
	v_exp_f32_e32 v166, v97
	v_mfma_f32_16x16x32_bf16 v[40:43], v[124:127], v[152:155], v[40:43]
	v_exp_f32_e32 v164, v98
	v_mfma_f32_16x16x32_bf16 v[44:47], v[112:115], v[156:159], v[44:47]
	v_exp_f32_e32 v165, v99
	v_mfma_f32_16x16x32_bf16 v[40:43], v[116:119], v[156:159], v[40:43]
	v_exp_f32_e32 v171, v100
	v_exp_f32_e32 v170, v101
	s_waitcnt lgkmcnt(8)
	ds_read_b64_tr_b16 v[136:137], v212 offset:3072
	ds_read_b64_tr_b16 v[138:139], v212 offset:7168
	ds_read_b64_tr_b16 v[148:149], v212 offset:11264
	ds_read_b64_tr_b16 v[150:151], v212 offset:15360
	v_mfma_f32_16x16x32_bf16 v[32:35], v[120:123], v[140:143], v[32:35]
	v_exp_f32_e32 v169, v102
	v_mfma_f32_16x16x32_bf16 v[36:39], v[124:127], v[140:143], v[36:39]
	v_exp_f32_e32 v168, v103
	v_mfma_f32_16x16x32_bf16 v[32:35], v[112:115], v[144:147], v[32:35]
	v_exp_f32_e32 v178, v108
	v_mfma_f32_16x16x32_bf16 v[36:39], v[116:119], v[144:147], v[36:39]
	v_exp_f32_e32 v179, v109
	v_exp_f32_e32 v177, v110
	s_waitcnt lgkmcnt(8)
	ds_read_b64_tr_b16 v[152:153], v213 offset:3072
	ds_read_b64_tr_b16 v[154:155], v213 offset:7168
	ds_read_b64_tr_b16 v[156:157], v213 offset:11264
	ds_read_b64_tr_b16 v[158:159], v213 offset:15360
	v_mfma_f32_16x16x32_bf16 v[20:23], v[120:123], v[240:243], v[20:23]
	v_exp_f32_e32 v176, v111
	v_mfma_f32_16x16x32_bf16 v[16:19], v[124:127], v[240:243], v[16:19]
	v_exp_f32_e32 v175, v80
	v_mfma_f32_16x16x32_bf16 v[20:23], v[112:115], v[244:247], v[20:23]
	v_exp_f32_e32 v174, v81
	v_mfma_f32_16x16x32_bf16 v[16:19], v[116:119], v[244:247], v[16:19]
	v_exp_f32_e32 v172, v82
	v_exp_f32_e32 v173, v83
	s_waitcnt lgkmcnt(8)
	v_mfma_f32_16x16x32_bf16 v[28:31], v[120:123], v[128:131], v[28:31]
	v_exp_f32_e32 v183, v88
	v_mfma_f32_16x16x32_bf16 v[24:27], v[124:127], v[128:131], v[24:27]
	v_exp_f32_e32 v182, v89
	v_mfma_f32_16x16x32_bf16 v[28:31], v[112:115], v[132:135], v[28:31]
	v_exp_f32_e32 v181, v90
	v_mfma_f32_16x16x32_bf16 v[24:27], v[116:119], v[132:135], v[24:27]
	v_exp_f32_e32 v180, v91
	s_waitcnt lgkmcnt(4)
	v_mfma_f32_16x16x32_bf16 v[12:15], v[120:123], v[136:139], v[12:15]
	v_exp_f32_e32 v186, v92
	v_mfma_f32_16x16x32_bf16 v[8:11], v[124:127], v[136:139], v[8:11]
	v_exp_f32_e32 v187, v93
	v_mfma_f32_16x16x32_bf16 v[12:15], v[112:115], v[148:151], v[12:15]
	v_exp_f32_e32 v185, v94
	v_mfma_f32_16x16x32_bf16 v[8:11], v[116:119], v[148:151], v[8:11]
	v_exp_f32_e32 v184, v95
	s_waitcnt lgkmcnt(0)
	v_exp_f32_e32 v191, v104
	v_exp_f32_e32 v190, v105
	v_exp_f32_e32 v189, v106
	v_exp_f32_e32 v188, v107
	s_waitcnt vmcnt(3)
	s_waitcnt lgkmcnt(0)
	s_add_i32 s0, s23, 1
	s_cmp_ge_i32 s0, s14
	s_mov_b64 s[0:1], -1
	s_barrier
	s_cbranch_scc1 .LBB0_368
	v_mfma_f32_16x16x32_bf16 v[4:7], v[120:123], v[152:155], v[4:7]
	v_mfma_f32_16x16x32_bf16 v[0:3], v[124:127], v[152:155], v[0:3]
	v_mfma_f32_16x16x32_bf16 v[4:7], v[112:115], v[156:159], v[4:7]
	v_mfma_f32_16x16x32_bf16 v[0:3], v[116:119], v[156:159], v[0:3]
	s_and_b32 s0, s20, 0x6000
	v_add_u32_e32 v84, s0, v229
	v_add_u32_e32 v86, v84, v230
	v_add_u32_e32 v87, v84, v231
	ds_read_b128 v[240:243], v228
	ds_read_b128 v[128:131], v86
	ds_read_b128 v[244:247], v228 offset:2048
	ds_read_b128 v[132:135], v87
	ds_read_b128 v[152:155], v228 offset:1024
	ds_read_b128 v[156:159], v228 offset:3072
	ds_read_b128 v[136:139], v86 offset:512
	ds_read_b128 v[148:151], v87 offset:512
	ds_read_b128 v[140:143], v86 offset:4096
	ds_read_b128 v[144:147], v87 offset:4096
	s_lshl_b32 s0, s22, 14
	v_add_u32_e32 v214, s0, v223
	v_add_u32_e32 v215, s0, v224
	v_cvt_pk_bf16_f32 v120, v162, v163
	v_cvt_pk_bf16_f32 v121, v161, v160
	v_cvt_pk_bf16_f32 v122, v167, v166
	v_cvt_pk_bf16_f32 v123, v164, v165
	v_cvt_pk_bf16_f32 v112, v171, v170
	v_cvt_pk_bf16_f32 v113, v169, v168
	v_cvt_pk_bf16_f32 v114, v178, v179
	v_cvt_pk_bf16_f32 v115, v177, v176
	v_cvt_pk_bf16_f32 v124, v175, v174
	v_cvt_pk_bf16_f32 v125, v172, v173
	v_cvt_pk_bf16_f32 v126, v183, v182
	v_cvt_pk_bf16_f32 v127, v181, v180
	v_cvt_pk_bf16_f32 v116, v186, v187
	v_cvt_pk_bf16_f32 v117, v185, v184
	v_cvt_pk_bf16_f32 v118, v191, v190
	v_cvt_pk_bf16_f32 v119, v189, v188
	s_andn2_b64 vcc, exec, s[12:13]
	s_cbranch_vccz .Lh2a_resc

.LBB0_390:
	s_waitcnt lgkmcnt(8)
	ds_read_b64_tr_b16 v[160:161], v214 offset:2048
	ds_read_b64_tr_b16 v[162:163], v214 offset:6144
	ds_read_b64_tr_b16 v[164:165], v214 offset:10240
	ds_read_b64_tr_b16 v[166:167], v214 offset:14336
	v_mfma_f32_16x16x32_bf16 v[52:55], v[120:123], v[176:179], v[52:55]
	v_exp_f32_e32 v241, v84
	v_mfma_f32_16x16x32_bf16 v[48:51], v[124:127], v[176:179], v[48:51]
	v_exp_f32_e32 v244, v85
	v_mfma_f32_16x16x32_bf16 v[52:55], v[112:115], v[180:183], v[52:55]
	v_exp_f32_e32 v245, v86
	v_mfma_f32_16x16x32_bf16 v[48:51], v[116:119], v[180:183], v[48:51]
	v_exp_f32_e32 v247, v87
	v_exp_f32_e32 v240, v96
	s_waitcnt lgkmcnt(8)
	ds_read_b64_tr_b16 v[168:169], v215 offset:2048
	ds_read_b64_tr_b16 v[170:171], v215 offset:6144
	ds_read_b64_tr_b16 v[172:173], v215 offset:10240
	ds_read_b64_tr_b16 v[174:175], v215 offset:14336
	v_mfma_f32_16x16x32_bf16 v[44:47], v[120:123], v[184:187], v[44:47]
	v_exp_f32_e32 v242, v97
	v_mfma_f32_16x16x32_bf16 v[40:43], v[124:127], v[184:187], v[40:43]
	v_exp_f32_e32 v243, v98
	v_mfma_f32_16x16x32_bf16 v[44:47], v[112:115], v[188:191], v[44:47]
	v_exp_f32_e32 v246, v99
	v_mfma_f32_16x16x32_bf16 v[40:43], v[116:119], v[188:191], v[40:43]
	v_exp_f32_e32 v137, v80
	v_exp_f32_e32 v148, v81
	s_waitcnt lgkmcnt(8)
	ds_read_b64_tr_b16 v[176:177], v214 offset:3072
	ds_read_b64_tr_b16 v[178:179], v214 offset:7168
	ds_read_b64_tr_b16 v[180:181], v214 offset:11264
	ds_read_b64_tr_b16 v[182:183], v214 offset:15360
	v_mfma_f32_16x16x32_bf16 v[32:35], v[120:123], v[140:143], v[32:35]
	v_exp_f32_e32 v149, v82
	v_mfma_f32_16x16x32_bf16 v[36:39], v[124:127], v[140:143], v[36:39]
	v_exp_f32_e32 v151, v83
	v_mfma_f32_16x16x32_bf16 v[32:35], v[112:115], v[144:147], v[32:35]
	v_exp_f32_e32 v136, v89
	v_mfma_f32_16x16x32_bf16 v[36:39], v[116:119], v[144:147], v[36:39]
	v_exp_f32_e32 v139, v90
	v_exp_f32_e32 v150, v91
	s_waitcnt lgkmcnt(8)
	ds_read_b64_tr_b16 v[184:185], v215 offset:3072
	ds_read_b64_tr_b16 v[186:187], v215 offset:7168
	ds_read_b64_tr_b16 v[188:189], v215 offset:11264
	ds_read_b64_tr_b16 v[190:191], v215 offset:15360
	v_mfma_f32_16x16x32_bf16 v[20:23], v[120:123], v[160:163], v[20:23]
	v_exp_f32_e32 v129, v92
	v_mfma_f32_16x16x32_bf16 v[16:19], v[124:127], v[160:163], v[16:19]
	v_exp_f32_e32 v138, v95
	v_mfma_f32_16x16x32_bf16 v[20:23], v[112:115], v[164:167], v[20:23]
	v_exp_f32_e32 v128, v104
	v_mfma_f32_16x16x32_bf16 v[16:19], v[116:119], v[164:167], v[16:19]
	v_exp_f32_e32 v130, v105
	v_exp_f32_e32 v131, v106
	s_waitcnt lgkmcnt(8)
	v_mfma_f32_16x16x32_bf16 v[28:31], v[120:123], v[168:171], v[28:31]
	v_exp_f32_e32 v153, v100
	v_mfma_f32_16x16x32_bf16 v[24:27], v[124:127], v[168:171], v[24:27]
	v_exp_f32_e32 v152, v108
	v_mfma_f32_16x16x32_bf16 v[28:31], v[112:115], v[172:175], v[28:31]
	v_exp_f32_e32 v154, v109
	v_mfma_f32_16x16x32_bf16 v[24:27], v[116:119], v[172:175], v[24:27]
	v_exp_f32_e32 v155, v110
	s_waitcnt lgkmcnt(4)
	v_mfma_f32_16x16x32_bf16 v[12:15], v[120:123], v[176:179], v[12:15]
	v_exp_f32_e32 v156, v101
	v_mfma_f32_16x16x32_bf16 v[8:11], v[124:127], v[176:179], v[8:11]
	v_exp_f32_e32 v158, v102
	v_mfma_f32_16x16x32_bf16 v[12:15], v[112:115], v[180:183], v[12:15]
	v_exp_f32_e32 v159, v103
	v_mfma_f32_16x16x32_bf16 v[8:11], v[116:119], v[180:183], v[8:11]
	v_exp_f32_e32 v157, v111
	s_waitcnt lgkmcnt(0)
	v_exp_f32_e32 v132, v88
	v_exp_f32_e32 v134, v93
	v_exp_f32_e32 v135, v94
	v_exp_f32_e32 v133, v107
	s_waitcnt vmcnt(3)
	s_waitcnt lgkmcnt(0)
	s_add_i32 s19, s19, 0x8000
	s_addk_i32 s20, 0x4000
	s_cmp_ge_i32 s21, s14
	s_cselect_b64 s[0:1], -1, 0
	s_and_b64 vcc, exec, s[0:1]
	s_mov_b32 s23, s21
	s_barrier
	s_cbranch_vccz .Lh1a_top
	v_mfma_f32_16x16x32_bf16 v[4:7], v[120:123], v[184:187], v[4:7]
	v_mfma_f32_16x16x32_bf16 v[0:3], v[124:127], v[184:187], v[0:3]
	v_mfma_f32_16x16x32_bf16 v[4:7], v[112:115], v[188:191], v[4:7]
	v_mfma_f32_16x16x32_bf16 v[0:3], v[116:119], v[188:191], v[0:3]
	s_branch .LBB0_392

.LBB0_395:
	v_mfma_f32_16x16x32_bf16 v[4:7], v[120:123], v[152:155], v[4:7]
	v_mfma_f32_16x16x32_bf16 v[0:3], v[124:127], v[152:155], v[0:3]
	v_mfma_f32_16x16x32_bf16 v[4:7], v[112:115], v[156:159], v[4:7]
	v_mfma_f32_16x16x32_bf16 v[0:3], v[116:119], v[156:159], v[0:3]
	s_and_b64 vcc, exec, s[0:1]
	s_mov_b32 s19, s17
	s_cbranch_vccnz .LBB0_419

.LBB0_400:
	s_waitcnt lgkmcnt(8)
	ds_read_b64_tr_b16 v[240:241], v212 offset:2048
	ds_read_b64_tr_b16 v[242:243], v212 offset:6144
	ds_read_b64_tr_b16 v[244:245], v212 offset:10240
	ds_read_b64_tr_b16 v[246:247], v212 offset:14336
	v_mfma_f32_16x16x32_bf16 v[52:55], v[120:123], v[136:139], v[52:55]
	v_exp_f32_e32 v162, v84
	v_mfma_f32_16x16x32_bf16 v[48:51], v[124:127], v[136:139], v[48:51]
	v_exp_f32_e32 v163, v85
	v_mfma_f32_16x16x32_bf16 v[52:55], v[112:115], v[148:151], v[52:55]
	v_exp_f32_e32 v161, v86
	v_mfma_f32_16x16x32_bf16 v[48:51], v[116:119], v[148:151], v[48:51]
	v_exp_f32_e32 v160, v87
	v_exp_f32_e32 v167, v96
	s_waitcnt lgkmcnt(8)
	ds_read_b64_tr_b16 v[128:129], v213 offset:2048
	ds_read_b64_tr_b16 v[130:131], v213 offset:6144
	ds_read_b64_tr_b16 v[132:133], v213 offset:10240
	ds_read_b64_tr_b16 v[134:135], v213 offset:14336
	v_mfma_f32_16x16x32_bf16 v[44:47], v[120:123], v[152:155], v[44:47]
	v_exp_f32_e32 v166, v97
	v_mfma_f32_16x16x32_bf16 v[40:43], v[124:127], v[152:155], v[40:43]
	v_exp_f32_e32 v164, v98
	v_mfma_f32_16x16x32_bf16 v[44:47], v[112:115], v[156:159], v[44:47]
	v_exp_f32_e32 v165, v99
	v_mfma_f32_16x16x32_bf16 v[40:43], v[116:119], v[156:159], v[40:43]
	v_exp_f32_e32 v171, v100
	v_exp_f32_e32 v170, v101
	s_waitcnt lgkmcnt(8)
	ds_read_b64_tr_b16 v[136:137], v212 offset:3072
	ds_read_b64_tr_b16 v[138:139], v212 offset:7168
	ds_read_b64_tr_b16 v[148:149], v212 offset:11264
	ds_read_b64_tr_b16 v[150:151], v212 offset:15360
	v_mfma_f32_16x16x32_bf16 v[32:35], v[120:123], v[140:143], v[32:35]
	v_exp_f32_e32 v169, v102
	v_mfma_f32_16x16x32_bf16 v[36:39], v[124:127], v[140:143], v[36:39]
	v_exp_f32_e32 v168, v103
	v_mfma_f32_16x16x32_bf16 v[32:35], v[112:115], v[144:147], v[32:35]
	v_exp_f32_e32 v178, v108
	v_mfma_f32_16x16x32_bf16 v[36:39], v[116:119], v[144:147], v[36:39]
	v_exp_f32_e32 v179, v109
	v_exp_f32_e32 v177, v110
	s_waitcnt lgkmcnt(8)
	ds_read_b64_tr_b16 v[152:153], v213 offset:3072
	ds_read_b64_tr_b16 v[154:155], v213 offset:7168
	ds_read_b64_tr_b16 v[156:157], v213 offset:11264
	ds_read_b64_tr_b16 v[158:159], v213 offset:15360
	v_mfma_f32_16x16x32_bf16 v[20:23], v[120:123], v[240:243], v[20:23]
	v_exp_f32_e32 v176, v111
	v_mfma_f32_16x16x32_bf16 v[16:19], v[124:127], v[240:243], v[16:19]
	v_exp_f32_e32 v175, v80
	v_mfma_f32_16x16x32_bf16 v[20:23], v[112:115], v[244:247], v[20:23]
	v_exp_f32_e32 v174, v81
	v_mfma_f32_16x16x32_bf16 v[16:19], v[116:119], v[244:247], v[16:19]
	v_exp_f32_e32 v172, v82
	v_exp_f32_e32 v173, v83
	s_waitcnt lgkmcnt(8)
	v_mfma_f32_16x16x32_bf16 v[28:31], v[120:123], v[128:131], v[28:31]
	v_exp_f32_e32 v183, v88
	v_mfma_f32_16x16x32_bf16 v[24:27], v[124:127], v[128:131], v[24:27]
	v_exp_f32_e32 v182, v89
	v_mfma_f32_16x16x32_bf16 v[28:31], v[112:115], v[132:135], v[28:31]
	v_exp_f32_e32 v181, v90
	v_mfma_f32_16x16x32_bf16 v[24:27], v[116:119], v[132:135], v[24:27]
	v_exp_f32_e32 v180, v91
	s_waitcnt lgkmcnt(4)
	v_mfma_f32_16x16x32_bf16 v[12:15], v[120:123], v[136:139], v[12:15]
	v_exp_f32_e32 v186, v92
	v_mfma_f32_16x16x32_bf16 v[8:11], v[124:127], v[136:139], v[8:11]
	v_exp_f32_e32 v187, v93
	v_mfma_f32_16x16x32_bf16 v[12:15], v[112:115], v[148:151], v[12:15]
	v_exp_f32_e32 v185, v94
	v_mfma_f32_16x16x32_bf16 v[8:11], v[116:119], v[148:151], v[8:11]
	v_exp_f32_e32 v184, v95
	s_waitcnt lgkmcnt(0)
	v_exp_f32_e32 v191, v104
	v_exp_f32_e32 v190, v105
	v_exp_f32_e32 v189, v106
	v_exp_f32_e32 v188, v107
	s_waitcnt vmcnt(3)
	s_waitcnt lgkmcnt(0)
	s_add_i32 s0, s19, 1
	s_cmp_ge_i32 s0, s14
	s_mov_b64 s[0:1], -1
	s_barrier
	s_cbranch_scc1 .LBB0_395
	v_mfma_f32_16x16x32_bf16 v[4:7], v[120:123], v[152:155], v[4:7]
	v_mfma_f32_16x16x32_bf16 v[0:3], v[124:127], v[152:155], v[0:3]
	v_mfma_f32_16x16x32_bf16 v[4:7], v[112:115], v[156:159], v[4:7]
	v_mfma_f32_16x16x32_bf16 v[0:3], v[116:119], v[156:159], v[0:3]
	s_and_b32 s0, s16, 0x6000
	v_add_u32_e32 v84, s0, v229
	v_add_u32_e32 v86, v84, v230
	v_add_u32_e32 v87, v84, v231
	ds_read_b128 v[240:243], v228
	ds_read_b128 v[128:131], v86
	ds_read_b128 v[244:247], v228 offset:2048
	ds_read_b128 v[132:135], v87
	ds_read_b128 v[152:155], v228 offset:1024
	ds_read_b128 v[156:159], v228 offset:3072
	ds_read_b128 v[136:139], v86 offset:512
	ds_read_b128 v[148:151], v87 offset:512
	ds_read_b128 v[140:143], v86 offset:4096
	ds_read_b128 v[144:147], v87 offset:4096
	s_lshl_b32 s0, s18, 14
	v_add_u32_e32 v214, s0, v223
	v_add_u32_e32 v215, s0, v224
	v_cvt_pk_bf16_f32 v120, v162, v163
	v_cvt_pk_bf16_f32 v121, v161, v160
	v_cvt_pk_bf16_f32 v122, v167, v166
	v_cvt_pk_bf16_f32 v123, v164, v165
	v_cvt_pk_bf16_f32 v112, v171, v170
	v_cvt_pk_bf16_f32 v113, v169, v168
	v_cvt_pk_bf16_f32 v114, v178, v179
	v_cvt_pk_bf16_f32 v115, v177, v176
	v_cvt_pk_bf16_f32 v124, v175, v174
	v_cvt_pk_bf16_f32 v125, v172, v173
	v_cvt_pk_bf16_f32 v126, v183, v182
	v_cvt_pk_bf16_f32 v127, v181, v180
	v_cvt_pk_bf16_f32 v116, v186, v187
	v_cvt_pk_bf16_f32 v117, v185, v184
	v_cvt_pk_bf16_f32 v118, v191, v190
	v_cvt_pk_bf16_f32 v119, v189, v188
	s_andn2_b64 vcc, exec, s[10:11]
	s_cbranch_vccz .Lh2b_resc

.LBB0_417:
	s_waitcnt lgkmcnt(8)
	ds_read_b64_tr_b16 v[160:161], v214 offset:2048
	ds_read_b64_tr_b16 v[162:163], v214 offset:6144
	ds_read_b64_tr_b16 v[164:165], v214 offset:10240
	ds_read_b64_tr_b16 v[166:167], v214 offset:14336
	v_mfma_f32_16x16x32_bf16 v[52:55], v[120:123], v[176:179], v[52:55]
	v_exp_f32_e32 v241, v84
	v_mfma_f32_16x16x32_bf16 v[48:51], v[124:127], v[176:179], v[48:51]
	v_exp_f32_e32 v244, v85
	v_mfma_f32_16x16x32_bf16 v[52:55], v[112:115], v[180:183], v[52:55]
	v_exp_f32_e32 v245, v86
	v_mfma_f32_16x16x32_bf16 v[48:51], v[116:119], v[180:183], v[48:51]
	v_exp_f32_e32 v247, v87
	v_exp_f32_e32 v240, v96
	s_waitcnt lgkmcnt(8)
	ds_read_b64_tr_b16 v[168:169], v215 offset:2048
	ds_read_b64_tr_b16 v[170:171], v215 offset:6144
	ds_read_b64_tr_b16 v[172:173], v215 offset:10240
	ds_read_b64_tr_b16 v[174:175], v215 offset:14336
	v_mfma_f32_16x16x32_bf16 v[44:47], v[120:123], v[184:187], v[44:47]
	v_exp_f32_e32 v242, v97
	v_mfma_f32_16x16x32_bf16 v[40:43], v[124:127], v[184:187], v[40:43]
	v_exp_f32_e32 v243, v98
	v_mfma_f32_16x16x32_bf16 v[44:47], v[112:115], v[188:191], v[44:47]
	v_exp_f32_e32 v246, v99
	v_mfma_f32_16x16x32_bf16 v[40:43], v[116:119], v[188:191], v[40:43]
	v_exp_f32_e32 v137, v80
	v_exp_f32_e32 v148, v81
	s_waitcnt lgkmcnt(8)
	ds_read_b64_tr_b16 v[176:177], v214 offset:3072
	ds_read_b64_tr_b16 v[178:179], v214 offset:7168
	ds_read_b64_tr_b16 v[180:181], v214 offset:11264
	ds_read_b64_tr_b16 v[182:183], v214 offset:15360
	v_mfma_f32_16x16x32_bf16 v[32:35], v[120:123], v[140:143], v[32:35]
	v_exp_f32_e32 v149, v82
	v_mfma_f32_16x16x32_bf16 v[36:39], v[124:127], v[140:143], v[36:39]
	v_exp_f32_e32 v151, v83
	v_mfma_f32_16x16x32_bf16 v[32:35], v[112:115], v[144:147], v[32:35]
	v_exp_f32_e32 v136, v89
	v_mfma_f32_16x16x32_bf16 v[36:39], v[116:119], v[144:147], v[36:39]
	v_exp_f32_e32 v139, v90
	v_exp_f32_e32 v150, v91
	s_waitcnt lgkmcnt(8)
	ds_read_b64_tr_b16 v[184:185], v215 offset:3072
	ds_read_b64_tr_b16 v[186:187], v215 offset:7168
	ds_read_b64_tr_b16 v[188:189], v215 offset:11264
	ds_read_b64_tr_b16 v[190:191], v215 offset:15360
	v_mfma_f32_16x16x32_bf16 v[20:23], v[120:123], v[160:163], v[20:23]
	v_exp_f32_e32 v129, v92
	v_mfma_f32_16x16x32_bf16 v[16:19], v[124:127], v[160:163], v[16:19]
	v_exp_f32_e32 v138, v95
	v_mfma_f32_16x16x32_bf16 v[20:23], v[112:115], v[164:167], v[20:23]
	v_exp_f32_e32 v128, v104
	v_mfma_f32_16x16x32_bf16 v[16:19], v[116:119], v[164:167], v[16:19]
	v_exp_f32_e32 v130, v105
	v_exp_f32_e32 v131, v106
	s_waitcnt lgkmcnt(8)
	v_mfma_f32_16x16x32_bf16 v[28:31], v[120:123], v[168:171], v[28:31]
	v_exp_f32_e32 v153, v100
	v_mfma_f32_16x16x32_bf16 v[24:27], v[124:127], v[168:171], v[24:27]
	v_exp_f32_e32 v152, v108
	v_mfma_f32_16x16x32_bf16 v[28:31], v[112:115], v[172:175], v[28:31]
	v_exp_f32_e32 v154, v109
	v_mfma_f32_16x16x32_bf16 v[24:27], v[116:119], v[172:175], v[24:27]
	v_exp_f32_e32 v155, v110
	s_waitcnt lgkmcnt(4)
	v_mfma_f32_16x16x32_bf16 v[12:15], v[120:123], v[176:179], v[12:15]
	v_exp_f32_e32 v156, v101
	v_mfma_f32_16x16x32_bf16 v[8:11], v[124:127], v[176:179], v[8:11]
	v_exp_f32_e32 v158, v102
	v_mfma_f32_16x16x32_bf16 v[12:15], v[112:115], v[180:183], v[12:15]
	v_exp_f32_e32 v159, v103
	v_mfma_f32_16x16x32_bf16 v[8:11], v[116:119], v[180:183], v[8:11]
	v_exp_f32_e32 v157, v111
	s_waitcnt lgkmcnt(0)
	v_exp_f32_e32 v132, v88
	v_exp_f32_e32 v134, v93
	v_exp_f32_e32 v135, v94
	v_exp_f32_e32 v133, v107
	s_waitcnt vmcnt(3)
	s_waitcnt lgkmcnt(0)
	s_add_i32 s15, s15, 0x8000
	s_addk_i32 s16, 0x4000
	s_cmp_ge_i32 s17, s14
	s_cselect_b64 s[0:1], -1, 0
	s_and_b64 vcc, exec, s[0:1]
	s_mov_b32 s19, s17
	s_barrier
	s_cbranch_vccz .Lh1b_top
	v_mfma_f32_16x16x32_bf16 v[4:7], v[120:123], v[184:187], v[4:7]
	v_mfma_f32_16x16x32_bf16 v[0:3], v[124:127], v[184:187], v[0:3]
	v_mfma_f32_16x16x32_bf16 v[4:7], v[112:115], v[188:191], v[4:7]
	v_mfma_f32_16x16x32_bf16 v[0:3], v[116:119], v[188:191], v[0:3]
	s_branch .LBB0_419
